# grid barrier: non-leader workgroups poll the top-level generation word directly (per-XCD release hop removed)
# baseline (speedup 1.0000x reference)
.LBB0_1120:
	s_or_b64 exec, exec, s[24:25]
	v_cvt_f32_u32_e32 v5, v3
	s_waitcnt vmcnt(0)
	v_readfirstlane_b32 s24, v4
	v_sub_u32_e32 v4, 0, v3
	v_rcp_iflag_f32_e32 v5, v5
	v_add_u32_e32 v6, s24, v0
	v_mul_f32_e32 v5, 0x4f7ffffe, v5
	v_cvt_u32_f32_e32 v5, v5
	v_mul_lo_u32 v0, v4, v5
	v_mul_hi_u32 v0, v5, v0
	v_add_u32_e32 v0, v5, v0
	v_mul_hi_u32 v0, v6, v0
	v_mul_lo_u32 v4, v0, v3
	v_sub_u32_e32 v4, v6, v4
	v_add_u32_e32 v5, 1, v0
	v_cmp_ge_u32_e32 vcc, v4, v3
	s_nop 1
	v_cndmask_b32_e32 v0, v0, v5, vcc
	v_sub_u32_e32 v5, v4, v3
	v_cndmask_b32_e32 v4, v4, v5, vcc
	v_add_u32_e32 v5, 1, v0
	v_cmp_ge_u32_e32 vcc, v4, v3
	v_add_u32_e32 v4, 1, v6
	s_nop 0
	v_cndmask_b32_e32 v0, v0, v5, vcc
	v_mul_lo_u32 v5, v3, v0
	v_add_u32_e32 v3, v5, v3
	v_cmp_ne_u32_e32 vcc, v4, v3
	s_and_saveexec_b64 s[24:25], vcc
	s_xor_b64 s[24:25], exec, s[24:25]
	s_cbranch_execz .LBB0_1134
	v_readlane_b32 s6, v253, 0
	v_readlane_b32 s7, v253, 1
	s_waitcnt lgkmcnt(0)
	s_nop 3
	global_load_dword v2, v1, s[6:7] sc1
	s_waitcnt vmcnt(0)
	v_cmp_eq_u32_e32 vcc, v2, v0
	s_and_saveexec_b64 s[26:27], vcc
	s_cbranch_execz .LBB0_1133
	s_mov_b32 s28, 1
	s_mov_b64 s[30:31], 0
	s_branch .LBB0_1124

.LBB0_1151:
	s_or_b64 exec, exec, s[24:25]
	s_mov_b64 s[24:25], exec
	v_mbcnt_lo_u32_b32 v0, s24, 0
	v_mbcnt_hi_u32_b32 v0, s25, v0
	v_cmp_eq_u32_e32 vcc, 0, v0
	s_waitcnt vmcnt(0)
	buffer_inv sc1
	s_and_saveexec_b64 s[26:27], vcc
	s_cbranch_execz .LBB0_1153
	s_bcnt1_i32_b64 s24, s[24:25]
	v_readlane_b32 s6, v252, 60
	v_mov_b32_e32 v0, s24
	v_readlane_b32 s7, v252, 61
	s_nop 4
	s_nop 0
